# obuf_v80 + hand-written hg_prep gate loop + GDN scan fragment-read hoist
# baseline (speedup 1.0000x reference)
.LBB0_908:
	v_lshl_add_u64 v[190:191], v[188:189], 0, s[6:7]
	v_cvt_pk_bf16_f32 v164, v164, v165
	v_cvt_pk_bf16_f32 v165, v166, v167
	v_cvt_pk_bf16_f32 v167, v170, v171
	v_cvt_pk_bf16_f32 v170, v160, v161
	v_add_co_u32_e32 v160, vcc, s11, v190
	v_cvt_pk_bf16_f32 v166, v168, v169
	v_cvt_pk_bf16_f32 v168, v172, v173
	v_cvt_pk_bf16_f32 v169, v174, v175
	v_cvt_pk_bf16_f32 v171, v162, v163
	v_addc_co_u32_e32 v161, vcc, 0, v191, vcc
	ds_write_b64 v193, v[164:165]
	ds_write_b64 v193, v[166:167] offset:2304
	ds_write_b64 v193, v[168:169] offset:4608
	ds_write_b64 v194, v[170:171]
	global_store_dwordx4 v[160:161], v[164:167], off
	global_store_dwordx4 v[160:161], v[168:171], off offset:16
	s_waitcnt lgkmcnt(0)
	s_barrier
	ds_read_b128 v[206:209], v195
	ds_read_b128 v[210:213], v195 offset:64
	ds_read_b128 v[214:217], v195 offset:2304
	ds_read_b128 v[218:221], v195 offset:2368
	ds_read_b128 v[222:225], v195 offset:4608
	ds_read_b128 v[226:229], v195 offset:4672
	ds_read_b128 v[230:233], v196
	ds_read_b128 v[234:237], v196 offset:64
	s_waitcnt vmcnt(16)
	v_lshlrev_b32_e32 v160, 16, v12
	v_and_b32_e32 v161, 0xffff0000, v12
	v_lshlrev_b32_e32 v162, 16, v13
	v_and_b32_e32 v163, 0xffff0000, v13
	s_waitcnt lgkmcnt(7)
	s_nop 0
	v_mfma_f32_16x16x32_bf16 v[160:163], v[0:3], v[206:209], v[160:163]
	v_lshlrev_b32_e32 v164, 16, v14
	v_and_b32_e32 v165, 0xffff0000, v14
	v_lshlrev_b32_e32 v166, 16, v15
	s_waitcnt lgkmcnt(6)
	v_mfma_f32_16x16x32_bf16 v[160:163], v[4:7], v[210:213], v[160:163]
	v_and_b32_e32 v167, 0xffff0000, v15
	s_cmpk_lt_u32 s34, 0x76
	s_waitcnt lgkmcnt(5)
	v_mfma_f32_16x16x32_bf16 v[164:167], v[0:3], v[214:217], v[164:167]
	v_lshlrev_b32_e32 v168, 16, v8
	v_and_b32_e32 v169, 0xffff0000, v8
	v_lshlrev_b32_e32 v170, 16, v9
	s_waitcnt lgkmcnt(4)
	v_mfma_f32_16x16x32_bf16 v[164:167], v[4:7], v[218:221], v[164:167]
	v_and_b32_e32 v171, 0xffff0000, v9
	s_cselect_b64 s[8:9], -1, 0
	s_and_b64 vcc, exec, s[8:9]
	s_waitcnt lgkmcnt(3)
	v_mfma_f32_16x16x32_bf16 v[168:171], v[0:3], v[222:225], v[168:171]
	v_lshlrev_b32_e32 v172, 16, v10
	v_and_b32_e32 v173, 0xffff0000, v10
	v_lshlrev_b32_e32 v174, 16, v11
	s_waitcnt lgkmcnt(2)
	v_mfma_f32_16x16x32_bf16 v[168:171], v[4:7], v[226:229], v[168:171]
	v_and_b32_e32 v175, 0xffff0000, v11
	s_nop 0
	s_waitcnt lgkmcnt(1)
	v_mfma_f32_16x16x32_bf16 v[172:175], v[0:3], v[230:233], v[172:175]
	s_waitcnt lgkmcnt(0)
	v_mfma_f32_16x16x32_bf16 v[172:175], v[4:7], v[234:237], v[172:175]
	s_cbranch_vccz .LBB0_910
	s_add_i32 s0, s4, 0xffff7000
	s_lshl_b64 s[24:25], s[0:1], 1
	v_lshl_add_u64 v[4:5], v[176:177], 0, s[24:25]
	v_lshl_add_u64 v[12:13], v[178:179], 0, s[24:25]
	global_load_dwordx4 v[0:3], v[4:5], off
	s_nop 0
	global_load_dwordx4 v[4:7], v[4:5], off offset:64
	s_nop 0
	global_load_dwordx4 v[8:11], v[12:13], off offset:16
	s_nop 0
	global_load_dwordx4 v[12:15], v[12:13], off
.LBB0_910:
	v_cvt_pk_bf16_f32 v160, v160, v161
	v_cvt_pk_bf16_f32 v161, v162, v163
	v_cvt_pk_bf16_f32 v162, v164, v165
	v_cvt_pk_bf16_f32 v164, v168, v169
	v_add_co_u32_e32 v168, vcc, s12, v190
	v_cvt_pk_bf16_f32 v163, v166, v167
	v_cvt_pk_bf16_f32 v165, v170, v171
	v_cvt_pk_bf16_f32 v166, v172, v173
	v_cvt_pk_bf16_f32 v167, v174, v175
	v_addc_co_u32_e32 v169, vcc, 0, v191, vcc
	ds_write_b64 v193, v[160:161] offset:9216
	ds_write_b64 v193, v[162:163] offset:11520
	ds_write_b64 v193, v[164:165] offset:13824
	ds_write_b64 v194, v[166:167] offset:9216
	global_store_dwordx4 v[168:169], v[160:163], off
	global_store_dwordx4 v[168:169], v[164:167], off offset:16
	s_waitcnt lgkmcnt(0)
	s_barrier
	ds_read_b128 v[206:209], v195 offset:9216
	ds_read_b128 v[210:213], v195 offset:9280
	ds_read_b128 v[214:217], v195 offset:11520
	ds_read_b128 v[218:221], v195 offset:11584
	ds_read_b128 v[222:225], v195 offset:13824
	ds_read_b128 v[226:229], v195 offset:13888
	ds_read_b128 v[230:233], v196 offset:9216
	ds_read_b128 v[234:237], v196 offset:9280
	s_waitcnt vmcnt(16)
	v_lshlrev_b32_e32 v160, 16, v28
	v_and_b32_e32 v161, 0xffff0000, v28
	v_lshlrev_b32_e32 v162, 16, v29
	v_and_b32_e32 v163, 0xffff0000, v29
	s_waitcnt lgkmcnt(7)
	s_nop 0
	v_mfma_f32_16x16x32_bf16 v[160:163], v[16:19], v[206:209], v[160:163]
	v_lshlrev_b32_e32 v164, 16, v30
	v_and_b32_e32 v165, 0xffff0000, v30
	v_lshlrev_b32_e32 v166, 16, v31
	s_waitcnt lgkmcnt(6)
	v_mfma_f32_16x16x32_bf16 v[160:163], v[20:23], v[210:213], v[160:163]
	v_and_b32_e32 v167, 0xffff0000, v31
	s_andn2_b64 vcc, exec, s[8:9]
	s_waitcnt lgkmcnt(5)
	v_mfma_f32_16x16x32_bf16 v[164:167], v[16:19], v[214:217], v[164:167]
	v_lshlrev_b32_e32 v168, 16, v24
	v_and_b32_e32 v169, 0xffff0000, v24
	v_lshlrev_b32_e32 v170, 16, v25
	s_waitcnt lgkmcnt(4)
	v_mfma_f32_16x16x32_bf16 v[164:167], v[20:23], v[218:221], v[164:167]
	v_and_b32_e32 v171, 0xffff0000, v25
	s_nop 0
	s_waitcnt lgkmcnt(3)
	v_mfma_f32_16x16x32_bf16 v[168:171], v[16:19], v[222:225], v[168:171]
	v_lshlrev_b32_e32 v172, 16, v26
	v_and_b32_e32 v173, 0xffff0000, v26
	v_lshlrev_b32_e32 v174, 16, v27
	s_waitcnt lgkmcnt(2)
	v_mfma_f32_16x16x32_bf16 v[168:171], v[20:23], v[226:229], v[168:171]
	v_and_b32_e32 v175, 0xffff0000, v27
	s_nop 0
	s_waitcnt lgkmcnt(1)
	v_mfma_f32_16x16x32_bf16 v[172:175], v[16:19], v[230:233], v[172:175]
	s_waitcnt lgkmcnt(0)
	v_mfma_f32_16x16x32_bf16 v[172:175], v[20:23], v[234:237], v[172:175]
	s_cbranch_vccnz .LBB0_912
	s_add_i32 s0, s4, 0xffff8000
	s_lshl_b64 s[8:9], s[0:1], 1
	v_lshl_add_u64 v[20:21], v[176:177], 0, s[8:9]
	v_lshl_add_u64 v[28:29], v[178:179], 0, s[8:9]
	global_load_dwordx4 v[16:19], v[20:21], off
	s_nop 0
	global_load_dwordx4 v[20:23], v[20:21], off offset:64
	s_nop 0
	global_load_dwordx4 v[24:27], v[28:29], off offset:16
	s_nop 0
	global_load_dwordx4 v[28:31], v[28:29], off
.LBB0_912:
	v_cvt_pk_bf16_f32 v160, v160, v161
	v_cvt_pk_bf16_f32 v161, v162, v163
	v_cvt_pk_bf16_f32 v162, v164, v165
	v_cvt_pk_bf16_f32 v164, v168, v169
	v_add_co_u32_e32 v168, vcc, s13, v190
	v_cvt_pk_bf16_f32 v163, v166, v167
	v_cvt_pk_bf16_f32 v165, v170, v171
	v_cvt_pk_bf16_f32 v166, v172, v173
	v_cvt_pk_bf16_f32 v167, v174, v175
	v_addc_co_u32_e32 v169, vcc, 0, v191, vcc
	ds_write_b64 v193, v[160:161]
	ds_write_b64 v193, v[162:163] offset:2304
	ds_write_b64 v193, v[164:165] offset:4608
	ds_write_b64 v194, v[166:167]
	global_store_dwordx4 v[168:169], v[160:163], off
	global_store_dwordx4 v[168:169], v[164:167], off offset:16
	s_waitcnt lgkmcnt(0)
	s_barrier
	ds_read_b128 v[206:209], v195
	ds_read_b128 v[210:213], v195 offset:64
	ds_read_b128 v[214:217], v195 offset:2304
	ds_read_b128 v[218:221], v195 offset:2368
	ds_read_b128 v[222:225], v195 offset:4608
	ds_read_b128 v[226:229], v195 offset:4672
	ds_read_b128 v[230:233], v196
	ds_read_b128 v[234:237], v196 offset:64
	s_waitcnt vmcnt(16)
	v_lshlrev_b32_e32 v160, 16, v44
	v_and_b32_e32 v161, 0xffff0000, v44
	v_lshlrev_b32_e32 v162, 16, v45
	v_and_b32_e32 v163, 0xffff0000, v45
	s_waitcnt lgkmcnt(7)
	s_nop 0
	v_mfma_f32_16x16x32_bf16 v[160:163], v[32:35], v[206:209], v[160:163]
	v_lshlrev_b32_e32 v164, 16, v46
	v_and_b32_e32 v165, 0xffff0000, v46
	v_lshlrev_b32_e32 v166, 16, v47
	s_waitcnt lgkmcnt(6)
	v_mfma_f32_16x16x32_bf16 v[160:163], v[36:39], v[210:213], v[160:163]
	v_and_b32_e32 v167, 0xffff0000, v47
	s_cmpk_gt_u32 s34, 0x73
	s_waitcnt lgkmcnt(5)
	v_mfma_f32_16x16x32_bf16 v[164:167], v[32:35], v[214:217], v[164:167]
	v_lshlrev_b32_e32 v168, 16, v40
	v_and_b32_e32 v169, 0xffff0000, v40
	v_lshlrev_b32_e32 v170, 16, v41
	s_waitcnt lgkmcnt(4)
	v_mfma_f32_16x16x32_bf16 v[164:167], v[36:39], v[218:221], v[164:167]
	v_and_b32_e32 v171, 0xffff0000, v41
	s_nop 0
	s_waitcnt lgkmcnt(3)
	v_mfma_f32_16x16x32_bf16 v[168:171], v[32:35], v[222:225], v[168:171]
	v_lshlrev_b32_e32 v172, 16, v42
	v_and_b32_e32 v173, 0xffff0000, v42
	v_lshlrev_b32_e32 v174, 16, v43
	s_waitcnt lgkmcnt(2)
	v_mfma_f32_16x16x32_bf16 v[168:171], v[36:39], v[226:229], v[168:171]
	v_and_b32_e32 v175, 0xffff0000, v43
	s_nop 0
	s_waitcnt lgkmcnt(1)
	v_mfma_f32_16x16x32_bf16 v[172:175], v[32:35], v[230:233], v[172:175]
	s_waitcnt lgkmcnt(0)
	v_mfma_f32_16x16x32_bf16 v[172:175], v[36:39], v[234:237], v[172:175]
	s_cbranch_scc1 .LBB0_914
	s_add_i32 s0, s4, 0xffff9000
	s_lshl_b64 s[8:9], s[0:1], 1
	v_lshl_add_u64 v[36:37], v[176:177], 0, s[8:9]
	v_lshl_add_u64 v[44:45], v[178:179], 0, s[8:9]
	global_load_dwordx4 v[32:35], v[36:37], off
	s_nop 0
	global_load_dwordx4 v[36:39], v[36:37], off offset:64
	s_nop 0
	global_load_dwordx4 v[40:43], v[44:45], off offset:16
	s_nop 0
	global_load_dwordx4 v[44:47], v[44:45], off
.LBB0_914:
	v_cvt_pk_bf16_f32 v160, v160, v161
	v_cvt_pk_bf16_f32 v161, v162, v163
	v_cvt_pk_bf16_f32 v162, v164, v165
	v_cvt_pk_bf16_f32 v164, v168, v169
	v_add_co_u32_e32 v168, vcc, s14, v190
	v_cvt_pk_bf16_f32 v163, v166, v167
	v_cvt_pk_bf16_f32 v165, v170, v171
	v_cvt_pk_bf16_f32 v166, v172, v173
	v_cvt_pk_bf16_f32 v167, v174, v175
	v_addc_co_u32_e32 v169, vcc, 0, v191, vcc
	ds_write_b64 v193, v[160:161] offset:9216
	ds_write_b64 v193, v[162:163] offset:11520
	ds_write_b64 v193, v[164:165] offset:13824
	ds_write_b64 v194, v[166:167] offset:9216
	global_store_dwordx4 v[168:169], v[160:163], off
	global_store_dwordx4 v[168:169], v[164:167], off offset:16
	s_waitcnt lgkmcnt(0)
	s_barrier
	ds_read_b128 v[206:209], v195 offset:9216
	ds_read_b128 v[210:213], v195 offset:9280
	ds_read_b128 v[214:217], v195 offset:11520
	ds_read_b128 v[218:221], v195 offset:11584
	ds_read_b128 v[222:225], v195 offset:13824
	ds_read_b128 v[226:229], v195 offset:13888
	ds_read_b128 v[230:233], v196 offset:9216
	ds_read_b128 v[234:237], v196 offset:9280
	s_waitcnt vmcnt(16)
	v_lshlrev_b32_e32 v160, 16, v60
	v_and_b32_e32 v161, 0xffff0000, v60
	v_lshlrev_b32_e32 v162, 16, v61
	v_and_b32_e32 v163, 0xffff0000, v61
	s_waitcnt lgkmcnt(7)
	s_nop 0
	v_mfma_f32_16x16x32_bf16 v[160:163], v[48:51], v[206:209], v[160:163]
	v_lshlrev_b32_e32 v164, 16, v62
	v_and_b32_e32 v165, 0xffff0000, v62
	v_lshlrev_b32_e32 v166, 16, v63
	s_waitcnt lgkmcnt(6)
	v_mfma_f32_16x16x32_bf16 v[160:163], v[52:55], v[210:213], v[160:163]
	v_and_b32_e32 v167, 0xffff0000, v63
	s_cmpk_gt_u32 s34, 0x72
	s_waitcnt lgkmcnt(5)
	v_mfma_f32_16x16x32_bf16 v[164:167], v[48:51], v[214:217], v[164:167]
	v_lshlrev_b32_e32 v168, 16, v56
	v_and_b32_e32 v169, 0xffff0000, v56
	v_lshlrev_b32_e32 v170, 16, v57
	s_waitcnt lgkmcnt(4)
	v_mfma_f32_16x16x32_bf16 v[164:167], v[52:55], v[218:221], v[164:167]
	v_and_b32_e32 v171, 0xffff0000, v57
	s_nop 0
	s_waitcnt lgkmcnt(3)
	v_mfma_f32_16x16x32_bf16 v[168:171], v[48:51], v[222:225], v[168:171]
	v_lshlrev_b32_e32 v172, 16, v58
	v_and_b32_e32 v173, 0xffff0000, v58
	v_lshlrev_b32_e32 v174, 16, v59
	s_waitcnt lgkmcnt(2)
	v_mfma_f32_16x16x32_bf16 v[168:171], v[52:55], v[226:229], v[168:171]
	v_and_b32_e32 v175, 0xffff0000, v59
	s_nop 0
	s_waitcnt lgkmcnt(1)
	v_mfma_f32_16x16x32_bf16 v[172:175], v[48:51], v[230:233], v[172:175]
	s_waitcnt lgkmcnt(0)
	v_mfma_f32_16x16x32_bf16 v[172:175], v[52:55], v[234:237], v[172:175]
	s_cbranch_scc1 .LBB0_916
	s_add_i32 s0, s4, 0xffffa000
	s_lshl_b64 s[8:9], s[0:1], 1
	v_lshl_add_u64 v[52:53], v[176:177], 0, s[8:9]
	v_lshl_add_u64 v[60:61], v[178:179], 0, s[8:9]
	global_load_dwordx4 v[48:51], v[52:53], off
	s_nop 0
	global_load_dwordx4 v[52:55], v[52:53], off offset:64
	s_nop 0
	global_load_dwordx4 v[56:59], v[60:61], off offset:16
	s_nop 0
	global_load_dwordx4 v[60:63], v[60:61], off
.LBB0_916:
	v_cvt_pk_bf16_f32 v160, v160, v161
	v_cvt_pk_bf16_f32 v161, v162, v163
	v_cvt_pk_bf16_f32 v162, v164, v165
	v_cvt_pk_bf16_f32 v164, v168, v169
	v_add_co_u32_e32 v168, vcc, s15, v190
	v_cvt_pk_bf16_f32 v163, v166, v167
	v_cvt_pk_bf16_f32 v165, v170, v171
	v_cvt_pk_bf16_f32 v166, v172, v173
	v_cvt_pk_bf16_f32 v167, v174, v175
	v_addc_co_u32_e32 v169, vcc, 0, v191, vcc
	ds_write_b64 v193, v[160:161]
	ds_write_b64 v193, v[162:163] offset:2304
	ds_write_b64 v193, v[164:165] offset:4608
	ds_write_b64 v194, v[166:167]
	global_store_dwordx4 v[168:169], v[160:163], off
	global_store_dwordx4 v[168:169], v[164:167], off offset:16
	s_waitcnt lgkmcnt(0)
	s_barrier
	ds_read_b128 v[206:209], v195
	ds_read_b128 v[210:213], v195 offset:64
	ds_read_b128 v[214:217], v195 offset:2304
	ds_read_b128 v[218:221], v195 offset:2368
	ds_read_b128 v[222:225], v195 offset:4608
	ds_read_b128 v[226:229], v195 offset:4672
	ds_read_b128 v[230:233], v196
	ds_read_b128 v[234:237], v196 offset:64
	s_waitcnt vmcnt(16)
	v_lshlrev_b32_e32 v160, 16, v76
	v_and_b32_e32 v161, 0xffff0000, v76
	v_lshlrev_b32_e32 v162, 16, v77
	v_and_b32_e32 v163, 0xffff0000, v77
	s_waitcnt lgkmcnt(7)
	s_nop 0
	v_mfma_f32_16x16x32_bf16 v[160:163], v[64:67], v[206:209], v[160:163]
	v_lshlrev_b32_e32 v164, 16, v78
	v_and_b32_e32 v165, 0xffff0000, v78
	v_lshlrev_b32_e32 v166, 16, v79
	s_waitcnt lgkmcnt(6)
	v_mfma_f32_16x16x32_bf16 v[160:163], v[68:71], v[210:213], v[160:163]
	v_and_b32_e32 v167, 0xffff0000, v79
	s_cmpk_gt_u32 s34, 0x71
	s_waitcnt lgkmcnt(5)
	v_mfma_f32_16x16x32_bf16 v[164:167], v[64:67], v[214:217], v[164:167]
	v_lshlrev_b32_e32 v168, 16, v72
	v_and_b32_e32 v169, 0xffff0000, v72
	v_lshlrev_b32_e32 v170, 16, v73
	s_waitcnt lgkmcnt(4)
	v_mfma_f32_16x16x32_bf16 v[164:167], v[68:71], v[218:221], v[164:167]
	v_and_b32_e32 v171, 0xffff0000, v73
	s_nop 0
	s_waitcnt lgkmcnt(3)
	v_mfma_f32_16x16x32_bf16 v[168:171], v[64:67], v[222:225], v[168:171]
	v_lshlrev_b32_e32 v172, 16, v74
	v_and_b32_e32 v173, 0xffff0000, v74
	v_lshlrev_b32_e32 v174, 16, v75
	s_waitcnt lgkmcnt(2)
	v_mfma_f32_16x16x32_bf16 v[168:171], v[68:71], v[226:229], v[168:171]
	v_and_b32_e32 v175, 0xffff0000, v75
	s_nop 0
	s_waitcnt lgkmcnt(1)
	v_mfma_f32_16x16x32_bf16 v[172:175], v[64:67], v[230:233], v[172:175]
	s_waitcnt lgkmcnt(0)
	v_mfma_f32_16x16x32_bf16 v[172:175], v[68:71], v[234:237], v[172:175]
	s_cbranch_scc1 .LBB0_918
	s_add_i32 s0, s4, 0xffffb000
	s_lshl_b64 s[8:9], s[0:1], 1
	v_lshl_add_u64 v[68:69], v[176:177], 0, s[8:9]
	v_lshl_add_u64 v[76:77], v[178:179], 0, s[8:9]
	global_load_dwordx4 v[64:67], v[68:69], off
	s_nop 0
	global_load_dwordx4 v[68:71], v[68:69], off offset:64
	s_nop 0
	global_load_dwordx4 v[72:75], v[76:77], off offset:16
	s_nop 0
	global_load_dwordx4 v[76:79], v[76:77], off
.LBB0_918:
	v_cvt_pk_bf16_f32 v160, v160, v161
	v_cvt_pk_bf16_f32 v161, v162, v163
	v_cvt_pk_bf16_f32 v162, v164, v165
	v_cvt_pk_bf16_f32 v164, v168, v169
	v_add_co_u32_e32 v168, vcc, s16, v190
	v_cvt_pk_bf16_f32 v163, v166, v167
	v_cvt_pk_bf16_f32 v165, v170, v171
	v_cvt_pk_bf16_f32 v166, v172, v173
	v_cvt_pk_bf16_f32 v167, v174, v175
	v_addc_co_u32_e32 v169, vcc, 0, v191, vcc
	ds_write_b64 v193, v[160:161] offset:9216
	ds_write_b64 v193, v[162:163] offset:11520
	ds_write_b64 v193, v[164:165] offset:13824
	ds_write_b64 v194, v[166:167] offset:9216
	global_store_dwordx4 v[168:169], v[160:163], off
	global_store_dwordx4 v[168:169], v[164:167], off offset:16
	s_waitcnt lgkmcnt(0)
	s_barrier
	ds_read_b128 v[206:209], v195 offset:9216
	ds_read_b128 v[210:213], v195 offset:9280
	ds_read_b128 v[214:217], v195 offset:11520
	ds_read_b128 v[218:221], v195 offset:11584
	ds_read_b128 v[222:225], v195 offset:13824
	ds_read_b128 v[226:229], v195 offset:13888
	ds_read_b128 v[230:233], v196 offset:9216
	ds_read_b128 v[234:237], v196 offset:9280
	s_waitcnt vmcnt(16)
	v_lshlrev_b32_e32 v160, 16, v92
	v_and_b32_e32 v161, 0xffff0000, v92
	v_lshlrev_b32_e32 v162, 16, v93
	v_and_b32_e32 v163, 0xffff0000, v93
	s_waitcnt lgkmcnt(7)
	s_nop 0
	v_mfma_f32_16x16x32_bf16 v[160:163], v[80:83], v[206:209], v[160:163]
	v_lshlrev_b32_e32 v164, 16, v94
	v_and_b32_e32 v165, 0xffff0000, v94
	v_lshlrev_b32_e32 v166, 16, v95
	s_waitcnt lgkmcnt(6)
	v_mfma_f32_16x16x32_bf16 v[160:163], v[84:87], v[210:213], v[160:163]
	v_and_b32_e32 v167, 0xffff0000, v95
	s_cmpk_gt_u32 s34, 0x70
	s_waitcnt lgkmcnt(5)
	v_mfma_f32_16x16x32_bf16 v[164:167], v[80:83], v[214:217], v[164:167]
	v_lshlrev_b32_e32 v168, 16, v88
	v_and_b32_e32 v169, 0xffff0000, v88
	v_lshlrev_b32_e32 v170, 16, v89
	s_waitcnt lgkmcnt(4)
	v_mfma_f32_16x16x32_bf16 v[164:167], v[84:87], v[218:221], v[164:167]
	v_and_b32_e32 v171, 0xffff0000, v89
	s_nop 0
	s_waitcnt lgkmcnt(3)
	v_mfma_f32_16x16x32_bf16 v[168:171], v[80:83], v[222:225], v[168:171]
	v_lshlrev_b32_e32 v172, 16, v90
	v_and_b32_e32 v173, 0xffff0000, v90
	v_lshlrev_b32_e32 v174, 16, v91
	s_waitcnt lgkmcnt(2)
	v_mfma_f32_16x16x32_bf16 v[168:171], v[84:87], v[226:229], v[168:171]
	v_and_b32_e32 v175, 0xffff0000, v91
	s_nop 0
	s_waitcnt lgkmcnt(1)
	v_mfma_f32_16x16x32_bf16 v[172:175], v[80:83], v[230:233], v[172:175]
	s_waitcnt lgkmcnt(0)
	v_mfma_f32_16x16x32_bf16 v[172:175], v[84:87], v[234:237], v[172:175]
	s_cbranch_scc1 .LBB0_920
	s_add_i32 s0, s4, 0xffffc000
	s_lshl_b64 s[8:9], s[0:1], 1
	v_lshl_add_u64 v[84:85], v[176:177], 0, s[8:9]
	v_lshl_add_u64 v[92:93], v[178:179], 0, s[8:9]
	global_load_dwordx4 v[80:83], v[84:85], off
	s_nop 0
	global_load_dwordx4 v[84:87], v[84:85], off offset:64
	s_nop 0
	global_load_dwordx4 v[88:91], v[92:93], off offset:16
	s_nop 0
	global_load_dwordx4 v[92:95], v[92:93], off
.LBB0_920:
	v_cvt_pk_bf16_f32 v160, v160, v161
	v_cvt_pk_bf16_f32 v161, v162, v163
	v_cvt_pk_bf16_f32 v162, v164, v165
	v_cvt_pk_bf16_f32 v164, v168, v169
	v_add_co_u32_e32 v168, vcc, s17, v190
	v_cvt_pk_bf16_f32 v163, v166, v167
	v_cvt_pk_bf16_f32 v165, v170, v171
	v_cvt_pk_bf16_f32 v166, v172, v173
	v_cvt_pk_bf16_f32 v167, v174, v175
	v_addc_co_u32_e32 v169, vcc, 0, v191, vcc
	ds_write_b64 v193, v[160:161]
	ds_write_b64 v193, v[162:163] offset:2304
	ds_write_b64 v193, v[164:165] offset:4608
	ds_write_b64 v194, v[166:167]
	global_store_dwordx4 v[168:169], v[160:163], off
	global_store_dwordx4 v[168:169], v[164:167], off offset:16
	s_waitcnt lgkmcnt(0)
	s_barrier
	ds_read_b128 v[206:209], v195
	ds_read_b128 v[210:213], v195 offset:64
	ds_read_b128 v[214:217], v195 offset:2304
	ds_read_b128 v[218:221], v195 offset:2368
	ds_read_b128 v[222:225], v195 offset:4608
	ds_read_b128 v[226:229], v195 offset:4672
	ds_read_b128 v[230:233], v196
	ds_read_b128 v[234:237], v196 offset:64
	s_waitcnt vmcnt(16)
	v_lshlrev_b32_e32 v160, 16, v108
	v_and_b32_e32 v161, 0xffff0000, v108
	v_lshlrev_b32_e32 v162, 16, v109
	v_and_b32_e32 v163, 0xffff0000, v109
	s_waitcnt lgkmcnt(7)
	s_nop 0
	v_mfma_f32_16x16x32_bf16 v[160:163], v[96:99], v[206:209], v[160:163]
	v_lshlrev_b32_e32 v164, 16, v110
	v_and_b32_e32 v165, 0xffff0000, v110
	v_lshlrev_b32_e32 v166, 16, v111
	s_waitcnt lgkmcnt(6)
	v_mfma_f32_16x16x32_bf16 v[160:163], v[100:103], v[210:213], v[160:163]
	v_and_b32_e32 v167, 0xffff0000, v111
	s_cmpk_gt_u32 s34, 0x6f
	s_waitcnt lgkmcnt(5)
	v_mfma_f32_16x16x32_bf16 v[164:167], v[96:99], v[214:217], v[164:167]
	v_lshlrev_b32_e32 v168, 16, v104
	v_and_b32_e32 v169, 0xffff0000, v104
	v_lshlrev_b32_e32 v170, 16, v105
	s_waitcnt lgkmcnt(4)
	v_mfma_f32_16x16x32_bf16 v[164:167], v[100:103], v[218:221], v[164:167]
	v_and_b32_e32 v171, 0xffff0000, v105
	s_nop 0
	s_waitcnt lgkmcnt(3)
	v_mfma_f32_16x16x32_bf16 v[168:171], v[96:99], v[222:225], v[168:171]
	v_lshlrev_b32_e32 v172, 16, v106
	v_and_b32_e32 v173, 0xffff0000, v106
	v_lshlrev_b32_e32 v174, 16, v107
	s_waitcnt lgkmcnt(2)
	v_mfma_f32_16x16x32_bf16 v[168:171], v[100:103], v[226:229], v[168:171]
	v_and_b32_e32 v175, 0xffff0000, v107
	s_nop 0
	s_waitcnt lgkmcnt(1)
	v_mfma_f32_16x16x32_bf16 v[172:175], v[96:99], v[230:233], v[172:175]
	s_waitcnt lgkmcnt(0)
	v_mfma_f32_16x16x32_bf16 v[172:175], v[100:103], v[234:237], v[172:175]
	s_cbranch_scc1 .LBB0_922
	s_add_i32 s0, s4, 0xffffd000
	s_lshl_b64 s[8:9], s[0:1], 1
	v_lshl_add_u64 v[100:101], v[176:177], 0, s[8:9]
	v_lshl_add_u64 v[108:109], v[178:179], 0, s[8:9]
	global_load_dwordx4 v[96:99], v[100:101], off
	s_nop 0
	global_load_dwordx4 v[100:103], v[100:101], off offset:64
	s_nop 0
	global_load_dwordx4 v[104:107], v[108:109], off offset:16
	s_nop 0
	global_load_dwordx4 v[108:111], v[108:109], off
.LBB0_922:
	v_cvt_pk_bf16_f32 v160, v160, v161
	v_cvt_pk_bf16_f32 v161, v162, v163
	v_cvt_pk_bf16_f32 v162, v164, v165
	v_cvt_pk_bf16_f32 v164, v168, v169
	v_add_co_u32_e32 v168, vcc, s29, v190
	v_cvt_pk_bf16_f32 v163, v166, v167
	v_cvt_pk_bf16_f32 v165, v170, v171
	v_cvt_pk_bf16_f32 v166, v172, v173
	v_cvt_pk_bf16_f32 v167, v174, v175
	v_addc_co_u32_e32 v169, vcc, 0, v191, vcc
	ds_write_b64 v193, v[160:161] offset:9216
	ds_write_b64 v193, v[162:163] offset:11520
	ds_write_b64 v193, v[164:165] offset:13824
	ds_write_b64 v194, v[166:167] offset:9216
	global_store_dwordx4 v[168:169], v[160:163], off
	global_store_dwordx4 v[168:169], v[164:167], off offset:16
	s_waitcnt lgkmcnt(0)
	s_barrier
	ds_read_b128 v[206:209], v195 offset:9216
	ds_read_b128 v[210:213], v195 offset:9280
	ds_read_b128 v[214:217], v195 offset:11520
	ds_read_b128 v[218:221], v195 offset:11584
	ds_read_b128 v[222:225], v195 offset:13824
	ds_read_b128 v[226:229], v195 offset:13888
	ds_read_b128 v[230:233], v196 offset:9216
	ds_read_b128 v[234:237], v196 offset:9280
	s_waitcnt vmcnt(16)
	v_lshlrev_b32_e32 v160, 16, v124
	v_and_b32_e32 v161, 0xffff0000, v124
	v_lshlrev_b32_e32 v162, 16, v125
	v_and_b32_e32 v163, 0xffff0000, v125
	s_waitcnt lgkmcnt(7)
	s_nop 0
	v_mfma_f32_16x16x32_bf16 v[160:163], v[112:115], v[206:209], v[160:163]
	s_cmpk_gt_u32 s34, 0x6e
	s_waitcnt lgkmcnt(6)
	v_mfma_f32_16x16x32_bf16 v[164:167], v[116:119], v[210:213], v[160:163]
	s_nop 2
	v_lshlrev_b32_e32 v160, 16, v126
	v_and_b32_e32 v161, 0xffff0000, v126
	v_lshlrev_b32_e32 v162, 16, v127
	v_and_b32_e32 v163, 0xffff0000, v127
	s_nop 0
	s_waitcnt lgkmcnt(5)
	v_mfma_f32_16x16x32_bf16 v[160:163], v[112:115], v[214:217], v[160:163]
	s_waitcnt lgkmcnt(4)
	v_mfma_f32_16x16x32_bf16 v[168:171], v[116:119], v[218:221], v[160:163]
	s_nop 5
	v_lshlrev_b32_e32 v160, 16, v120
	v_and_b32_e32 v161, 0xffff0000, v120
	v_lshlrev_b32_e32 v162, 16, v121
	v_and_b32_e32 v163, 0xffff0000, v121
	s_nop 0
	s_waitcnt lgkmcnt(3)
	v_mfma_f32_16x16x32_bf16 v[160:163], v[112:115], v[222:225], v[160:163]
	s_waitcnt lgkmcnt(2)
	v_mfma_f32_16x16x32_bf16 v[172:175], v[116:119], v[226:229], v[160:163]
	s_nop 5
	v_lshlrev_b32_e32 v160, 16, v122
	v_and_b32_e32 v161, 0xffff0000, v122
	v_lshlrev_b32_e32 v162, 16, v123
	v_and_b32_e32 v163, 0xffff0000, v123
	s_nop 0
	s_waitcnt lgkmcnt(1)
	v_mfma_f32_16x16x32_bf16 v[160:163], v[112:115], v[230:233], v[160:163]
	s_waitcnt lgkmcnt(0)
	v_mfma_f32_16x16x32_bf16 v[160:163], v[116:119], v[234:237], v[160:163]
	s_cbranch_scc1 .LBB0_924
	s_add_i32 s0, s4, 0xffffe000
	s_lshl_b64 s[8:9], s[0:1], 1
	v_lshl_add_u64 v[116:117], v[176:177], 0, s[8:9]
	v_lshl_add_u64 v[124:125], v[178:179], 0, s[8:9]
	global_load_dwordx4 v[112:115], v[116:117], off
	s_nop 0
	global_load_dwordx4 v[116:119], v[116:117], off offset:64
	s_nop 0
	global_load_dwordx4 v[120:123], v[124:125], off offset:16
	s_nop 0
	global_load_dwordx4 v[124:127], v[124:125], off
.LBB0_924:
	s_cmpk_gt_u32 s34, 0x77
	s_cselect_b64 s[8:9], -1, 0
	s_and_b64 vcc, exec, s[8:9]
	s_cbranch_vccnz .LBB0_927
	s_add_i32 s0, s10, s6
	s_add_i32 s0, s0, 0x10000
	v_cvt_pk_bf16_f32 v164, v164, v165
	v_cvt_pk_bf16_f32 v165, v166, v167
	v_cvt_pk_bf16_f32 v166, v168, v169
	v_cvt_pk_bf16_f32 v167, v170, v171
	v_cvt_pk_bf16_f32 v168, v172, v173
	v_cvt_pk_bf16_f32 v169, v174, v175
	v_cvt_pk_bf16_f32 v170, v160, v161
	v_cvt_pk_bf16_f32 v171, v162, v163
	v_lshl_add_u64 v[160:161], v[186:187], 0, s[0:1]
	ds_write_b64 v193, v[164:165]
	ds_write_b64 v193, v[166:167] offset:2304
	ds_write_b64 v193, v[168:169] offset:4608
	ds_write_b64 v194, v[170:171]
	global_store_dwordx4 v[160:161], v[164:167], off
	global_store_dwordx4 v[160:161], v[168:171], off offset:16
	s_waitcnt lgkmcnt(0)
	s_barrier
	ds_read_b128 v[206:209], v195
	ds_read_b128 v[210:213], v195 offset:64
	ds_read_b128 v[214:217], v195 offset:2304
	ds_read_b128 v[218:221], v195 offset:2368
	ds_read_b128 v[222:225], v195 offset:4608
	ds_read_b128 v[226:229], v195 offset:4672
	ds_read_b128 v[230:233], v196
	ds_read_b128 v[234:237], v196 offset:64
	s_waitcnt vmcnt(22)
	v_lshlrev_b32_e32 v160, 16, v140
	v_and_b32_e32 v161, 0xffff0000, v140
	v_lshlrev_b32_e32 v162, 16, v141
	v_and_b32_e32 v163, 0xffff0000, v141
	s_waitcnt lgkmcnt(7)
	s_nop 0
	v_mfma_f32_16x16x32_bf16 v[160:163], v[128:131], v[206:209], v[160:163]
	s_cmpk_gt_u32 s34, 0x6d
	s_waitcnt lgkmcnt(6)
	v_mfma_f32_16x16x32_bf16 v[164:167], v[132:135], v[210:213], v[160:163]
	s_nop 2
	v_lshlrev_b32_e32 v160, 16, v142
	v_and_b32_e32 v161, 0xffff0000, v142
	v_lshlrev_b32_e32 v162, 16, v143
	v_and_b32_e32 v163, 0xffff0000, v143
	s_nop 0
	s_waitcnt lgkmcnt(5)
	v_mfma_f32_16x16x32_bf16 v[160:163], v[128:131], v[214:217], v[160:163]
	s_waitcnt lgkmcnt(4)
	v_mfma_f32_16x16x32_bf16 v[168:171], v[132:135], v[218:221], v[160:163]
	s_nop 5
	v_lshlrev_b32_e32 v160, 16, v136
	v_and_b32_e32 v161, 0xffff0000, v136
	v_lshlrev_b32_e32 v162, 16, v137
	v_and_b32_e32 v163, 0xffff0000, v137
	s_nop 0
	s_waitcnt lgkmcnt(3)
	v_mfma_f32_16x16x32_bf16 v[160:163], v[128:131], v[222:225], v[160:163]
	s_waitcnt lgkmcnt(2)
	v_mfma_f32_16x16x32_bf16 v[172:175], v[132:135], v[226:229], v[160:163]
	s_nop 5
	v_lshlrev_b32_e32 v160, 16, v138
	v_and_b32_e32 v161, 0xffff0000, v138
	v_lshlrev_b32_e32 v162, 16, v139
	v_and_b32_e32 v163, 0xffff0000, v139
	s_nop 0
	s_waitcnt lgkmcnt(1)
	v_mfma_f32_16x16x32_bf16 v[160:163], v[128:131], v[230:233], v[160:163]
	s_waitcnt lgkmcnt(0)
	v_mfma_f32_16x16x32_bf16 v[160:163], v[132:135], v[234:237], v[160:163]
	s_cbranch_scc1 .LBB0_927
	s_add_i32 s0, s4, 0xfffff000
	s_lshl_b64 s[24:25], s[0:1], 1
	v_lshl_add_u64 v[132:133], v[176:177], 0, s[24:25]
	v_lshl_add_u64 v[140:141], v[178:179], 0, s[24:25]
	global_load_dwordx4 v[128:131], v[132:133], off
	s_nop 0
	global_load_dwordx4 v[132:135], v[132:133], off offset:64
	s_nop 0
	global_load_dwordx4 v[136:139], v[140:141], off offset:16
	s_nop 0
	global_load_dwordx4 v[140:143], v[140:141], off
.LBB0_927:
	s_cmpk_gt_u32 s34, 0x76
	s_cbranch_scc1 .LBB0_907
	s_add_i32 s0, s10, s6
	s_add_i32 s0, s0, 0x12000
	v_cvt_pk_bf16_f32 v164, v164, v165
	v_cvt_pk_bf16_f32 v165, v166, v167
	v_cvt_pk_bf16_f32 v166, v168, v169
	v_cvt_pk_bf16_f32 v167, v170, v171
	v_cvt_pk_bf16_f32 v168, v172, v173
	v_cvt_pk_bf16_f32 v169, v174, v175
	v_cvt_pk_bf16_f32 v170, v160, v161
	v_cvt_pk_bf16_f32 v171, v162, v163
	v_lshl_add_u64 v[160:161], v[186:187], 0, s[0:1]
	ds_write_b64 v193, v[164:165] offset:9216
	ds_write_b64 v193, v[166:167] offset:11520
	ds_write_b64 v193, v[168:169] offset:13824
	ds_write_b64 v194, v[170:171] offset:9216
	global_store_dwordx4 v[160:161], v[164:167], off
	global_store_dwordx4 v[160:161], v[168:171], off offset:16
	s_waitcnt lgkmcnt(0)
	s_barrier
	ds_read_b128 v[206:209], v195 offset:9216
	ds_read_b128 v[210:213], v195 offset:9280
	ds_read_b128 v[214:217], v195 offset:11520
	ds_read_b128 v[218:221], v195 offset:11584
	ds_read_b128 v[222:225], v195 offset:13824
	ds_read_b128 v[226:229], v195 offset:13888
	ds_read_b128 v[230:233], v196 offset:9216
	ds_read_b128 v[234:237], v196 offset:9280
	s_waitcnt vmcnt(18)
	v_lshlrev_b32_e32 v160, 16, v156
	v_and_b32_e32 v161, 0xffff0000, v156
	v_lshlrev_b32_e32 v162, 16, v157
	v_and_b32_e32 v163, 0xffff0000, v157
	s_waitcnt lgkmcnt(7)
	s_nop 0
	v_mfma_f32_16x16x32_bf16 v[160:163], v[144:147], v[206:209], v[160:163]
	s_cmpk_gt_u32 s34, 0x6c
	s_waitcnt lgkmcnt(6)
	v_mfma_f32_16x16x32_bf16 v[164:167], v[148:151], v[210:213], v[160:163]
	s_nop 2
	v_lshlrev_b32_e32 v160, 16, v158
	v_and_b32_e32 v161, 0xffff0000, v158
	v_lshlrev_b32_e32 v162, 16, v159
	v_and_b32_e32 v163, 0xffff0000, v159
	s_nop 0
	s_waitcnt lgkmcnt(5)
	v_mfma_f32_16x16x32_bf16 v[160:163], v[144:147], v[214:217], v[160:163]
	s_waitcnt lgkmcnt(4)
	v_mfma_f32_16x16x32_bf16 v[168:171], v[148:151], v[218:221], v[160:163]
	s_nop 5
	v_lshlrev_b32_e32 v160, 16, v152
	v_and_b32_e32 v161, 0xffff0000, v152
	v_lshlrev_b32_e32 v162, 16, v153
	v_and_b32_e32 v163, 0xffff0000, v153
	s_nop 0
	s_waitcnt lgkmcnt(3)
	v_mfma_f32_16x16x32_bf16 v[160:163], v[144:147], v[222:225], v[160:163]
	s_waitcnt lgkmcnt(2)
	v_mfma_f32_16x16x32_bf16 v[172:175], v[148:151], v[226:229], v[160:163]
	s_nop 5
	v_lshlrev_b32_e32 v160, 16, v154
	v_and_b32_e32 v161, 0xffff0000, v154
	v_lshlrev_b32_e32 v162, 16, v155
	v_and_b32_e32 v163, 0xffff0000, v155
	s_nop 0
	s_waitcnt lgkmcnt(1)
	v_mfma_f32_16x16x32_bf16 v[160:163], v[144:147], v[230:233], v[160:163]
	s_waitcnt lgkmcnt(0)
	v_mfma_f32_16x16x32_bf16 v[160:163], v[148:151], v[234:237], v[160:163]
	s_cbranch_scc1 .LBB0_907
	s_mov_b32 s5, s1
	s_lshl_b64 s[24:25], s[4:5], 1
	v_lshl_add_u64 v[148:149], v[176:177], 0, s[24:25]
	v_lshl_add_u64 v[156:157], v[178:179], 0, s[24:25]
	global_load_dwordx4 v[144:147], v[148:149], off
	s_nop 0
	global_load_dwordx4 v[148:151], v[148:149], off offset:64
	s_nop 0
	global_load_dwordx4 v[152:155], v[156:157], off offset:16
	s_nop 0
	global_load_dwordx4 v[156:159], v[156:157], off
	s_branch .LBB0_907
